# plus: pool unit weight and scale loads issued together instead of one round trip each
# speedup vs baseline: 1.0385x; 1.0044x over previous
; #define LAS __attribute__((address_space(3)))
; DI unsigned pack2(float lo, float hi) { f32x2 v = {lo, hi}; bf16x2_t b = __builtin_convertvector(v, bf16x2_t); return __builtin_bit_cast(unsigned, b); }
; DI void pool_unit(const Params& p, int li, int m0, int g, lchar* lds) {
;     ...
;         for (int r = 0; r < 16; ++r, ++t) {
;             const int lo = max(t - hw, 0), hi = min(t + hw, L);
;             const float ic = 1.0f / (float)(hi - lo);
;             const unsigned wc = up[(t - tl0 + 8) * 64];
;             const float d0 = s0 * ic - bf2f(wc & 0xffffu), d1 = s1 * ic - bf2f(wc >> 16);
;             *(LAS unsigned*)(Dt + (rs * 16 + r) * PSTR + cp * 4) = pack2(d0, d1);
;             const int ta = t + hw, tr = t - hw;
;             if (ta < L) { const unsigned w = up[(ta - tl0 + 8) * 64]; s0 += bf2f(w & 0xffffu); s1 += bf2f(w >> 16); }
;             if (tr >= 0) { const unsigned w = up[(tr - tl0 + 8) * 64]; s0 -= bf2f(w & 0xffffu); s1 -= bf2f(w >> 16); }
;         }
;     }
;     __syncthreads();
;     f32x16 acc[2];
;     { const float z0 = opaque0();
; #pragma unroll
;       for (int mt = 0; mt < 2; ++mt)
; #pragma unroll
;         for (int i = 0; i < 16; ++i) acc[mt][i] = z0; }
;     const bf16_t* W = p.wt_pool(li) + (size_t)g * 128 * 128;
; #pragma unroll
;     for (int ks = 0; ks < 8; ++ks) {
;         bf16x8 xf[2];
; #pragma unroll
;         for (int mt = 0; mt < 2; ++mt) xf[mt] = *(const LAS bf16x8*)(Dt + (wm * 64 + mt * 32 + l31) * PSTR + ks * 32 + h * 16);
;         const bf16x8 wf = *(const bf16x8*)(W + (size_t)(wn * 32 + l31) * 128 + ks * 16 + h * 8);
; #pragma unroll
;         for (int mt = 0; mt < 2; ++mt) acc[mt] = MFMA32(wf, xf[mt], acc[mt]);
;     }
;     const float* sc = p.pool_scale + li * 512 + g * 128 + wn * 32;
; #pragma unroll
;     for (int mt = 0; mt < 2; ++mt) {
;         const int row = m0 + wm * 64 + mt * 32 + l31;
;         bf16_t* rp = MIX + (size_t)row * D + g * 128 + wn * 32 + 4 * h;
; #pragma unroll
;         for (int gg = 0; gg < 4; ++gg) {
;             const f32x4 s4 = *(const f32x4*)(sc + 8 * gg + 4 * h);
;             u32x2 w;
;             w.x = pack2(acc[mt][4 * gg] * s4[0], acc[mt][4 * gg + 1] * s4[1]);
;             w.y = pack2(acc[mt][4 * gg + 2] * s4[2], acc[mt][4 * gg + 3] * s4[3]);
;             *(u32x2*)(rp + 8 * gg) = w;
;         }
;     }
;     __syncthreads();
.LBB0_222:
	s_or_b64 exec, exec, s[0:1]
	v_or_b32_e32 v7, 15, v4
	v_subrev_u32_e32 v4, s38, v7
	v_add_u32_e32 v8, s38, v7
	v_max_i32_e32 v4, 0, v4
	v_min_i32_e32 v8, s42, v8
	v_sub_u32_e32 v4, v8, v4
	v_cvt_f32_i32_e32 v4, v4
	v_subrev_u32_e32 v7, s41, v7
	v_lshl_or_b32 v3, v7, 8, v3
	ds_read_b32 v3, v3 offset:2048
	v_div_scale_f32 v8, s[0:1], v4, v4, 1.0
	v_rcp_f32_e32 v9, v8
	s_movk_i32 s30, 0xffe0
	s_lshl_b32 s0, s40, 15
	s_add_u32 s0, s23, s0
	v_fma_f32 v10, -v8, v9, 1.0
	v_fmac_f32_e32 v9, v10, v9
	v_div_scale_f32 v10, vcc, 1.0, v4, 1.0
	v_mul_f32_e32 v11, v10, v9
	v_fma_f32 v12, -v8, v11, v10
	v_fmac_f32_e32 v11, v12, v9
	v_fma_f32 v8, -v8, v11, v10
	v_div_fmas_f32 v8, v8, v9, v11
	v_div_fixup_f32 v4, v8, v4, 1.0
	s_waitcnt lgkmcnt(0)
	v_lshlrev_b32_e32 v8, 16, v3
	v_and_b32_e32 v9, 0xffff0000, v3
	v_pk_fma_f32 v[0:1], v[4:5], v[0:1], v[8:9] op_sel:[0,1,0] op_sel_hi:[0,0,1] neg_lo:[0,0,1] neg_hi:[0,0,1]
	v_cvt_pk_bf16_f32 v0, v0, v1
	v_lshrrev_b32_e32 v1, 5, v2
	v_ashrrev_i32_e32 v2, 2, v6
	v_and_b32_e32 v34, 0xffffffe0, v2
	v_bfi_b32 v2, s30, v2, v6
	v_ashrrev_i32_e32 v3, 31, v2
	s_addc_u32 s1, s26, 0
	v_lshlrev_b64 v[2:3], 8, v[2:3]
	v_lshlrev_b32_e32 v32, 4, v1
	v_lshl_add_u64 v[2:3], s[0:1], 0, v[2:3]
	v_mov_b32_e32 v33, v129
	v_lshl_add_u64 v[36:37], v[2:3], 0, v[32:33]
	ds_write_b32 v5, v0 offset:40944
	s_waitcnt lgkmcnt(0)
	s_barrier
	v_mov_b32 v0, 0
	global_load_dwordx4 v[60:63], v[36:37], off
	global_load_dwordx4 v[64:67], v[36:37], off offset:32
	global_load_dwordx4 v[68:71], v[36:37], off offset:64
	global_load_dwordx4 v[72:75], v[36:37], off offset:96
	global_load_dwordx4 v[76:79], v[36:37], off offset:128
	global_load_dwordx4 v[80:83], v[36:37], off offset:160
	global_load_dwordx4 v[84:87], v[36:37], off offset:192
	global_load_dwordx4 v[88:91], v[36:37], off offset:224
	v_and_b32_e32 v4, 0x5f, v6
	s_movk_i32 s0, 0x110
	v_mad_u32_u24 v35, v4, s0, v32
	ds_read_b128 v[38:41], v35 offset:45568
	ds_read_b128 v[46:49], v35 offset:36864
	ds_read_b128 v[50:53], v35 offset:36896
	v_and_b32_e32 v54, 31, v6
	v_and_b32_e32 v55, 64, v6
	v_lshlrev_b32_e32 v128, 3, v1
	v_mov_b32_e32 v1, v0
	v_mov_b32_e32 v2, v0
	v_mov_b32_e32 v3, v0
	v_mov_b32_e32 v4, v0
	v_mov_b32_e32 v5, v0
	v_mov_b32_e32 v6, v0
	v_mov_b32_e32 v7, v0
	v_mov_b32_e32 v8, v0
	v_mov_b32_e32 v9, v0
	v_mov_b32_e32 v10, v0
	v_mov_b32_e32 v11, v0
	v_mov_b32_e32 v12, v0
	v_mov_b32_e32 v13, v0
	v_mov_b32_e32 v14, v0
	v_mov_b32_e32 v15, v0
	s_lshl_b32 s0, s40, 9
	s_add_u32 s0, s27, s0
	s_addc_u32 s1, s36, 0
	v_readlane_b32 s30, v252, 43
	v_readlane_b32 s31, v252, 44
	s_waitcnt vmcnt(0) lgkmcnt(1)
	v_mfma_f32_32x32x16_bf16 v[16:31], v[60:63], v[46:49], v[0:15]
	v_mfma_f32_32x32x16_bf16 v[0:15], v[60:63], v[38:41], v[0:15]
	ds_read_b128 v[38:41], v35 offset:45600
	s_waitcnt lgkmcnt(1)
	v_mfma_f32_32x32x16_bf16 v[16:31], v[64:67], v[50:53], v[16:31]
	s_waitcnt lgkmcnt(0)
	v_mfma_f32_32x32x16_bf16 v[0:15], v[64:67], v[38:41], v[0:15]
	ds_read_b128 v[38:41], v35 offset:36928
	ds_read_b128 v[42:45], v35 offset:45632
	s_waitcnt lgkmcnt(1)
	v_mfma_f32_32x32x16_bf16 v[16:31], v[68:71], v[38:41], v[16:31]
	s_waitcnt lgkmcnt(0)
	v_mfma_f32_32x32x16_bf16 v[0:15], v[68:71], v[42:45], v[0:15]
	ds_read_b128 v[38:41], v35 offset:36960
	ds_read_b128 v[42:45], v35 offset:45664
	s_waitcnt lgkmcnt(1)
	v_mfma_f32_32x32x16_bf16 v[16:31], v[72:75], v[38:41], v[16:31]
	s_waitcnt lgkmcnt(0)
	v_mfma_f32_32x32x16_bf16 v[0:15], v[72:75], v[42:45], v[0:15]
	ds_read_b128 v[38:41], v35 offset:36992
	ds_read_b128 v[42:45], v35 offset:45696
	s_waitcnt lgkmcnt(1)
	v_mfma_f32_32x32x16_bf16 v[16:31], v[76:79], v[38:41], v[16:31]
	s_waitcnt lgkmcnt(0)
	v_mfma_f32_32x32x16_bf16 v[0:15], v[76:79], v[42:45], v[0:15]
	ds_read_b128 v[38:41], v35 offset:37024
	ds_read_b128 v[42:45], v35 offset:45728
	s_waitcnt lgkmcnt(1)
	v_mfma_f32_32x32x16_bf16 v[16:31], v[80:83], v[38:41], v[16:31]
	s_waitcnt lgkmcnt(0)
	v_mfma_f32_32x32x16_bf16 v[0:15], v[80:83], v[42:45], v[0:15]
	ds_read_b128 v[38:41], v35 offset:37056
	ds_read_b128 v[42:45], v35 offset:45760
	s_waitcnt lgkmcnt(1)
	v_mfma_f32_32x32x16_bf16 v[16:31], v[84:87], v[38:41], v[16:31]
	s_waitcnt lgkmcnt(0)
	v_mfma_f32_32x32x16_bf16 v[0:15], v[84:87], v[42:45], v[0:15]
	ds_read_b128 v[38:41], v35 offset:37088
	ds_read_b128 v[42:45], v35 offset:45792
	v_ashrrev_i32_e32 v35, 31, v34
	v_lshl_add_u64 v[36:37], v[34:35], 2, s[0:1]
	s_lshl_b32 s0, s40, 8
	s_add_u32 s0, s30, s0
	s_addc_u32 s1, s31, 0
	s_waitcnt lgkmcnt(1)
	v_mfma_f32_32x32x16_bf16 v[16:31], v[88:91], v[38:41], v[16:31]
	v_or3_b32 v38, v55, s37, v54
	v_lshl_add_u64 v[34:35], v[34:35], 1, s[0:1]
	v_ashrrev_i32_e32 v39, 31, v38
	v_lshl_add_u64 v[40:41], v[34:35], 0, v[128:129]
	v_lshl_add_u64 v[32:33], v[36:37], 0, v[32:33]
	global_load_dwordx4 v[92:95], v[32:33], off
	global_load_dwordx4 v[96:99], v[32:33], off offset:32
	global_load_dwordx4 v[100:103], v[32:33], off offset:64
	global_load_dwordx4 v[104:107], v[32:33], off offset:96
	v_lshlrev_b64 v[34:35], 11, v[38:39]
	s_add_i32 s22, s22, s2
	s_waitcnt lgkmcnt(0)
	v_mfma_f32_32x32x16_bf16 v[0:15], v[88:91], v[42:45], v[0:15]
	v_lshl_add_u64 v[42:43], v[40:41], 0, v[34:35]
	s_cmpk_gt_i32 s22, 0x87f
	s_waitcnt vmcnt(0)
	v_mul_f32_e64 v16, v16, v92
	v_mul_f32_e64 v17, v17, v93
	v_pk_mul_f32 v[18:19], v[18:19], v[94:95]
	v_cvt_pk_bf16_f32 v16, v16, v17
	v_cvt_pk_bf16_f32 v17, v18, v19
	global_store_dwordx2 v[42:43], v[16:17], off
	v_pk_mul_f32 v[16:17], v[20:21], v[96:97]
	v_pk_mul_f32 v[18:19], v[22:23], v[98:99]
	v_cvt_pk_bf16_f32 v16, v16, v17
	v_cvt_pk_bf16_f32 v17, v18, v19
	global_store_dwordx2 v[42:43], v[16:17], off offset:16
	v_pk_mul_f32 v[16:17], v[24:25], v[100:101]
	v_pk_mul_f32 v[18:19], v[26:27], v[102:103]
	v_cvt_pk_bf16_f32 v16, v16, v17
	v_cvt_pk_bf16_f32 v17, v18, v19
	global_store_dwordx2 v[42:43], v[16:17], off offset:32
	v_pk_mul_f32 v[16:17], v[28:29], v[104:105]
	v_pk_mul_f32 v[18:19], v[30:31], v[106:107]
	v_cvt_pk_bf16_f32 v16, v16, v17
	v_cvt_pk_bf16_f32 v17, v18, v19
	global_store_dwordx2 v[42:43], v[16:17], off offset:48
	v_or_b32_e32 v16, 32, v38
	v_ashrrev_i32_e32 v17, 31, v16
	v_lshlrev_b64 v[16:17], 11, v[16:17]
	v_lshl_add_u64 v[20:21], v[40:41], 0, v[16:17]
	v_pk_mul_f32 v[0:1], v[0:1], v[92:93]
	v_pk_mul_f32 v[2:3], v[2:3], v[94:95]
	v_cvt_pk_bf16_f32 v0, v0, v1
	v_cvt_pk_bf16_f32 v1, v2, v3
	global_store_dwordx2 v[20:21], v[0:1], off
	v_pk_mul_f32 v[0:1], v[4:5], v[96:97]
	v_pk_mul_f32 v[2:3], v[6:7], v[98:99]
	v_cvt_pk_bf16_f32 v0, v0, v1
	v_cvt_pk_bf16_f32 v1, v2, v3
	global_store_dwordx2 v[20:21], v[0:1], off offset:16
	v_pk_mul_f32 v[0:1], v[8:9], v[100:101]
	v_pk_mul_f32 v[2:3], v[10:11], v[102:103]
	v_cvt_pk_bf16_f32 v0, v0, v1
	v_cvt_pk_bf16_f32 v1, v2, v3
	global_store_dwordx2 v[20:21], v[0:1], off offset:32
	v_pk_mul_f32 v[0:1], v[12:13], v[104:105]
	v_pk_mul_f32 v[2:3], v[14:15], v[106:107]
	v_cvt_pk_bf16_f32 v0, v0, v1
	v_cvt_pk_bf16_f32 v1, v2, v3
	global_store_dwordx2 v[20:21], v[0:1], off offset:48
	s_barrier
	s_cbranch_scc1 .LBB0_292
